# v026 + attention item order rotated per workgroup (g = (k + bx mod 3) mod 3): the three dilation groups are processed concurrently across the chip instead of all workgroups being in the same group at
# baseline (speedup 1.0000x reference)
; __device__ __forceinline__ void phase(LAS unsigned char* lds, const bf16* QKV, bf16* Og, float* L2, int tid) {
;     for (int it = blockIdx.x; it < 768; it += gridDim.x) {
;         const int g = it >> 8, idx = it & 255;
;         int bl, h, r, dil, n0, cnt, nseg = 1;
;         if (g == 0) { const int strip = idx >> 3; bl = strip >> 3; h = strip & 7; r = 0; dil = 1; n0 = 4 * (idx & 7); cnt = 4; }
;         else if (g == 1) { const int strip = idx >> 1; bl = strip >> 5; h = (strip >> 2) & 7; r = strip & 3; dil = 4; n0 = 4 * (idx & 1); cnt = 4; }
;         else { bl = idx >> 6; h = (idx >> 3) & 7; r = 2 * (idx & 7); dil = 16; n0 = 0; cnt = 2; nseg = 2; }
.LBB0_280:
	s_mov_b32 s99, s25
	s_and_b32 s25, s99, 0xff
	s_mul_i32 s98, s25, 0xab
	s_lshr_b32 s98, s98, 9
	s_mul_i32 s98, s98, 3
	s_sub_i32 s98, s25, s98
	s_lshr_b32 s25, s99, 8
	s_add_i32 s98, s98, s25
	s_cmp_gt_u32 s98, 2
	s_cselect_b32 s25, 3, 0
	s_sub_i32 s98, s98, s25
	s_lshl_b32 s98, s98, 8
	s_and_b32 s25, s99, 0xff
	s_or_b32 s25, s25, s98
	s_ashr_i32 s0, s25, 8
	s_cmpk_gt_u32 s25, 0xff
	s_mov_b64 s[20:21], -1
	s_cbranch_scc0 .LBB0_287
	s_cmp_lg_u32 s0, 1
	s_cbranch_scc0 .LBB0_283
	s_lshl_b32 s1, s25, 1
	s_and_b32 s22, s1, 14
	s_mov_b64 s[20:21], 0
